# SO5: scan side work (waves 4-7 lora branch) hand-written with packed f32 pairs, zero rows by address, all MFMAs up front (on v39)
# baseline (speedup 1.0000x reference)
.LBB0_436:
	s_waitcnt vmcnt(0)
	s_or_b64 s[10:11], s[82:83], s[56:57]
	s_and_b64 vcc, exec, s[10:11]
	s_waitcnt lgkmcnt(0)
	s_barrier
	s_cbranch_vccnz .LBB0_438
	s_lshl_b32 s15, s49, 6
	s_sub_i32 s16, s63, s73
	s_add_i32 s17, s15, s0
	s_sub_i32 s18, s71, s17
	s_add_i32 s14, s15, s60
	s_sub_i32 s31, s71, s14
	s_and_b64 s[10:11], s[8:9], exec
	s_cselect_b32 s16, s15, s16
	s_cselect_b32 s17, s17, s18
	s_cselect_b32 s14, s14, s31
	v_lshrrev_b32_e32 v136, 3, v1
	v_and_b32_e32 v137, 7, v1
	v_lshlrev_b32_e32 v143, 4, v1
	v_mov_b32_e32 v144, 0
	v_mov_b32_e32 v145, 0
	v_mov_b32_e32 v146, 0
	v_mov_b32_e32 v147, 0
	v_add_u32_e32 v143, 0x22f00, v143
	v_lshlrev_b32_e32 v138, 4, v137
	v_add_u32_e32 v139, s17, v136
	v_add_u32_e32 v140, s14, v136
	ds_write_b128 v143, v[144:147]
	v_subrev_u32_e32 v98, s16, v139
	v_subrev_u32_e32 v99, s16, v140
	v_cmp_lt_i32_e32 vcc, 0, v139
	v_mad_u32_u24 v98, v98, s58, v138
	v_mad_u32_u24 v99, v99, s58, v138
	v_mov_b32_e32 v141, 0x1a580
	v_mov_b32_e32 v142, 0x1a080
	v_cndmask_b32_e32 v100, v141, v98, vcc
	v_cmp_gt_i32_e32 vcc, s33, v139
	v_lshlrev_b32_e32 v148, 5, v137
	v_add_u32_e32 v148, 0x22000, v148
	v_cndmask_b32_e32 v101, v142, v98, vcc
	v_cmp_lt_i32_e32 vcc, 0, v140
	ds_read_b128 v[168:171], v100 offset:35200
	ds_read_b128 v[172:175], v98 offset:35840
	ds_read_b128 v[176:179], v101 offset:36480
	ds_read_b128 v[192:195], v148 offset:768
	ds_read_b128 v[196:199], v148 offset:784
	v_cndmask_b32_e32 v220, v141, v99, vcc
	v_cmp_gt_i32_e32 vcc, s33, v140
	ds_read_b128 v[200:203], v148 offset:1024
	ds_read_b128 v[204:207], v148 offset:1040
	v_sub_u32_e32 v149, 7, v136
	v_cndmask_b32_e32 v221, v142, v99, vcc
	ds_read_b128 v[180:183], v100 offset:35328
	ds_read_b128 v[184:187], v98 offset:35968
	ds_read_b128 v[188:191], v101 offset:36608
	v_cndmask_b32_e64 v149, v149, v136, s[8:9]
	v_lshl_add_u32 v149, v149, 7, v138
	v_add_u32_e32 v222, s34, v149
	v_add_u32_e32 v223, s61, v149
	v_readlane_b32 s10, v255, 25
	v_readlane_b32 s11, v255, 26
	v_lshlrev_b32_e32 v150, 7, v1
	v_lshrrev_b32_e32 v152, 1, v1
	v_and_b32_e32 v150, 0x780, v150
	v_and_b32_e32 v152, -8, v152
	v_mov_b32_e32 v151, 0
	v_lshl_add_u32 v150, v152, 1, v150
	s_mov_b32 s31, s41
	v_lshl_add_u64 v[152:153], s[10:11], 0, v[150:151]
	v_mov_b32_e32 v164, 0x4038aa3b
	v_mov_b32_e32 v165, 0x4038aa3b
	v_lshl_add_u64 v[152:153], v[152:153], 0, s[30:31]
	s_movk_i32 s10, 0x1000
	s_mov_b32 s11, 0
	v_lshl_add_u64 v[154:155], v[152:153], 0, s[10:11]
	s_mov_b32 s10, 0x40000
	v_lshl_add_u64 v[156:157], v[152:153], 0, s[10:11]
	s_mov_b32 s10, 0x41000
	v_lshl_add_u64 v[158:159], v[152:153], 0, s[10:11]
	global_load_dwordx4 v[34:37], v[152:153], off
	global_load_dwordx4 v[38:41], v[152:153], off offset:64
	global_load_dwordx4 v[42:45], v[152:153], off offset:2048
	global_load_dwordx4 v[46:49], v[152:153], off offset:2112
	global_load_dwordx4 v[50:53], v[154:155], off
	global_load_dwordx4 v[54:57], v[154:155], off offset:64
	global_load_dwordx4 v[58:61], v[154:155], off offset:2048
	global_load_dwordx4 v[62:65], v[154:155], off offset:2112
	global_load_dwordx4 v[66:69], v[156:157], off
	global_load_dwordx4 v[70:73], v[156:157], off offset:64
	global_load_dwordx4 v[74:77], v[156:157], off offset:2048
	global_load_dwordx4 v[78:81], v[156:157], off offset:2112
	global_load_dwordx4 v[82:85], v[158:159], off
	global_load_dwordx4 v[86:89], v[158:159], off offset:64
	global_load_dwordx4 v[90:93], v[158:159], off offset:2048
	global_load_dwordx4 v[94:97], v[158:159], off offset:2112
	s_waitcnt lgkmcnt(7)
	v_lshlrev_b32_e32 v136, 16, v168
	v_and_b32_e32 v137, 0xffff0000, v168
	v_lshlrev_b32_e32 v138, 16, v176
	v_and_b32_e32 v139, 0xffff0000, v176
	v_lshlrev_b32_e32 v140, 16, v172
	v_and_b32_e32 v141, 0xffff0000, v172
	v_lshlrev_b32_e32 v142, 16, v169
	v_and_b32_e32 v143, 0xffff0000, v169
	v_lshlrev_b32_e32 v144, 16, v177
	v_and_b32_e32 v145, 0xffff0000, v177
	v_lshlrev_b32_e32 v146, 16, v173
	v_and_b32_e32 v147, 0xffff0000, v173
	v_lshlrev_b32_e32 v148, 16, v170
	v_and_b32_e32 v149, 0xffff0000, v170
	v_lshlrev_b32_e32 v150, 16, v178
	v_and_b32_e32 v151, 0xffff0000, v178
	v_lshlrev_b32_e32 v152, 16, v174
	v_and_b32_e32 v153, 0xffff0000, v174
	v_lshlrev_b32_e32 v154, 16, v171
	v_and_b32_e32 v155, 0xffff0000, v171
	v_lshlrev_b32_e32 v156, 16, v179
	v_and_b32_e32 v157, 0xffff0000, v179
	v_lshlrev_b32_e32 v158, 16, v175
	v_and_b32_e32 v159, 0xffff0000, v175
	ds_read_b128 v[168:171], v220 offset:35200
	ds_read_b128 v[172:175], v99 offset:35840
	ds_read_b128 v[176:179], v221 offset:36480
	v_pk_add_f32 v[136:137], v[138:139], v[136:137]
	v_pk_add_f32 v[142:143], v[144:145], v[142:143]
	v_pk_add_f32 v[148:149], v[150:151], v[148:149]
	v_pk_add_f32 v[154:155], v[156:157], v[154:155]
	v_pk_fma_f32 v[136:137], v[136:137], 0.5, v[140:141] op_sel_hi:[1,0,1] neg_lo:[0,0,1] neg_hi:[0,0,1]
	v_pk_fma_f32 v[142:143], v[142:143], 0.5, v[146:147] op_sel_hi:[1,0,1] neg_lo:[0,0,1] neg_hi:[0,0,1]
	v_pk_fma_f32 v[148:149], v[148:149], 0.5, v[152:153] op_sel_hi:[1,0,1] neg_lo:[0,0,1] neg_hi:[0,0,1]
	v_pk_fma_f32 v[154:155], v[154:155], 0.5, v[158:159] op_sel_hi:[1,0,1] neg_lo:[0,0,1] neg_hi:[0,0,1]
	s_waitcnt lgkmcnt(8)
	v_pk_fma_f32 v[140:141], v[192:193], v[136:137], v[140:141]
	v_pk_fma_f32 v[146:147], v[194:195], v[142:143], v[146:147]
	v_pk_fma_f32 v[152:153], v[196:197], v[148:149], v[152:153]
	v_pk_fma_f32 v[158:159], v[198:199], v[154:155], v[158:159]
	v_pk_mul_f32 v[140:141], v[140:141], v[164:165]
	v_pk_mul_f32 v[146:147], v[146:147], v[164:165]
	v_pk_mul_f32 v[152:153], v[152:153], v[164:165]
	v_pk_mul_f32 v[158:159], v[158:159], v[164:165]
	v_exp_f32_e32 v140, v140
	v_exp_f32_e32 v141, v141
	v_exp_f32_e32 v146, v146
	v_exp_f32_e32 v147, v147
	v_exp_f32_e32 v152, v152
	v_exp_f32_e32 v153, v153
	v_exp_f32_e32 v158, v158
	v_exp_f32_e32 v159, v159
	v_pk_add_f32 v[140:141], v[140:141], 1.0 op_sel_hi:[1,0]
	v_pk_add_f32 v[146:147], v[146:147], 1.0 op_sel_hi:[1,0]
	v_pk_add_f32 v[152:153], v[152:153], 1.0 op_sel_hi:[1,0]
	v_pk_add_f32 v[158:159], v[158:159], 1.0 op_sel_hi:[1,0]
	v_rcp_f32_e32 v140, v140
	v_rcp_f32_e32 v141, v141
	v_rcp_f32_e32 v146, v146
	v_rcp_f32_e32 v147, v147
	v_rcp_f32_e32 v152, v152
	v_rcp_f32_e32 v153, v153
	v_rcp_f32_e32 v158, v158
	v_rcp_f32_e32 v159, v159
	v_pk_fma_f32 v[140:141], v[140:141], 2.0, 1.0 op_sel_hi:[1,0,0] neg_lo:[1,0,0] neg_hi:[1,0,0]
	v_pk_fma_f32 v[146:147], v[146:147], 2.0, 1.0 op_sel_hi:[1,0,0] neg_lo:[1,0,0] neg_hi:[1,0,0]
	v_pk_fma_f32 v[152:153], v[152:153], 2.0, 1.0 op_sel_hi:[1,0,0] neg_lo:[1,0,0] neg_hi:[1,0,0]
	v_pk_fma_f32 v[158:159], v[158:159], 2.0, 1.0 op_sel_hi:[1,0,0] neg_lo:[1,0,0] neg_hi:[1,0,0]
	v_cvt_pk_bf16_f32 v160, v140, v141
	v_cvt_pk_bf16_f32 v161, v146, v147
	v_cvt_pk_bf16_f32 v162, v152, v153
	v_cvt_pk_bf16_f32 v163, v158, v159
	ds_write_b128 v222, v[160:163] offset:16384
	s_waitcnt lgkmcnt(4)
	v_lshlrev_b32_e32 v136, 16, v180
	v_and_b32_e32 v137, 0xffff0000, v180
	v_lshlrev_b32_e32 v138, 16, v188
	v_and_b32_e32 v139, 0xffff0000, v188
	v_lshlrev_b32_e32 v140, 16, v184
	v_and_b32_e32 v141, 0xffff0000, v184
	v_lshlrev_b32_e32 v142, 16, v181
	v_and_b32_e32 v143, 0xffff0000, v181
	v_lshlrev_b32_e32 v144, 16, v189
	v_and_b32_e32 v145, 0xffff0000, v189
	v_lshlrev_b32_e32 v146, 16, v185
	v_and_b32_e32 v147, 0xffff0000, v185
	v_lshlrev_b32_e32 v148, 16, v182
	v_and_b32_e32 v149, 0xffff0000, v182
	v_lshlrev_b32_e32 v150, 16, v190
	v_and_b32_e32 v151, 0xffff0000, v190
	v_lshlrev_b32_e32 v152, 16, v186
	v_and_b32_e32 v153, 0xffff0000, v186
	v_lshlrev_b32_e32 v154, 16, v183
	v_and_b32_e32 v155, 0xffff0000, v183
	v_lshlrev_b32_e32 v156, 16, v191
	v_and_b32_e32 v157, 0xffff0000, v191
	v_lshlrev_b32_e32 v158, 16, v187
	v_and_b32_e32 v159, 0xffff0000, v187
	ds_read_b128 v[180:183], v220 offset:35328
	ds_read_b128 v[184:187], v99 offset:35968
	ds_read_b128 v[188:191], v221 offset:36608
	v_pk_add_f32 v[136:137], v[138:139], v[136:137]
	v_pk_add_f32 v[142:143], v[144:145], v[142:143]
	v_pk_add_f32 v[148:149], v[150:151], v[148:149]
	v_pk_add_f32 v[154:155], v[156:157], v[154:155]
	v_pk_fma_f32 v[136:137], v[136:137], 0.5, v[140:141] op_sel_hi:[1,0,1] neg_lo:[0,0,1] neg_hi:[0,0,1]
	v_pk_fma_f32 v[142:143], v[142:143], 0.5, v[146:147] op_sel_hi:[1,0,1] neg_lo:[0,0,1] neg_hi:[0,0,1]
	v_pk_fma_f32 v[148:149], v[148:149], 0.5, v[152:153] op_sel_hi:[1,0,1] neg_lo:[0,0,1] neg_hi:[0,0,1]
	v_pk_fma_f32 v[154:155], v[154:155], 0.5, v[158:159] op_sel_hi:[1,0,1] neg_lo:[0,0,1] neg_hi:[0,0,1]
	v_pk_fma_f32 v[140:141], v[200:201], v[136:137], v[140:141]
	v_pk_fma_f32 v[146:147], v[202:203], v[142:143], v[146:147]
	v_pk_fma_f32 v[152:153], v[204:205], v[148:149], v[152:153]
	v_pk_fma_f32 v[158:159], v[206:207], v[154:155], v[158:159]
	v_cvt_pk_bf16_f32 v216, v140, v141
	v_cvt_pk_bf16_f32 v217, v146, v147
	v_cvt_pk_bf16_f32 v218, v152, v153
	v_cvt_pk_bf16_f32 v219, v158, v159
	ds_write_b128 v222, v[216:219] offset:24576
	s_waitcnt lgkmcnt(5)
	v_lshlrev_b32_e32 v136, 16, v168
	v_and_b32_e32 v137, 0xffff0000, v168
	v_lshlrev_b32_e32 v138, 16, v176
	v_and_b32_e32 v139, 0xffff0000, v176
	v_lshlrev_b32_e32 v140, 16, v172
	v_and_b32_e32 v141, 0xffff0000, v172
	v_lshlrev_b32_e32 v142, 16, v169
	v_and_b32_e32 v143, 0xffff0000, v169
	v_lshlrev_b32_e32 v144, 16, v177
	v_and_b32_e32 v145, 0xffff0000, v177
	v_lshlrev_b32_e32 v146, 16, v173
	v_and_b32_e32 v147, 0xffff0000, v173
	v_lshlrev_b32_e32 v148, 16, v170
	v_and_b32_e32 v149, 0xffff0000, v170
	v_lshlrev_b32_e32 v150, 16, v178
	v_and_b32_e32 v151, 0xffff0000, v178
	v_lshlrev_b32_e32 v152, 16, v174
	v_and_b32_e32 v153, 0xffff0000, v174
	v_lshlrev_b32_e32 v154, 16, v171
	v_and_b32_e32 v155, 0xffff0000, v171
	v_lshlrev_b32_e32 v156, 16, v179
	v_and_b32_e32 v157, 0xffff0000, v179
	v_lshlrev_b32_e32 v158, 16, v175
	v_and_b32_e32 v159, 0xffff0000, v175
	v_pk_add_f32 v[136:137], v[138:139], v[136:137]
	v_pk_add_f32 v[142:143], v[144:145], v[142:143]
	v_pk_add_f32 v[148:149], v[150:151], v[148:149]
	v_pk_add_f32 v[154:155], v[156:157], v[154:155]
	v_pk_fma_f32 v[136:137], v[136:137], 0.5, v[140:141] op_sel_hi:[1,0,1] neg_lo:[0,0,1] neg_hi:[0,0,1]
	v_pk_fma_f32 v[142:143], v[142:143], 0.5, v[146:147] op_sel_hi:[1,0,1] neg_lo:[0,0,1] neg_hi:[0,0,1]
	v_pk_fma_f32 v[148:149], v[148:149], 0.5, v[152:153] op_sel_hi:[1,0,1] neg_lo:[0,0,1] neg_hi:[0,0,1]
	v_pk_fma_f32 v[154:155], v[154:155], 0.5, v[158:159] op_sel_hi:[1,0,1] neg_lo:[0,0,1] neg_hi:[0,0,1]
	v_pk_fma_f32 v[140:141], v[192:193], v[136:137], v[140:141]
	v_pk_fma_f32 v[146:147], v[194:195], v[142:143], v[146:147]
	v_pk_fma_f32 v[152:153], v[196:197], v[148:149], v[152:153]
	v_pk_fma_f32 v[158:159], v[198:199], v[154:155], v[158:159]
	v_pk_mul_f32 v[140:141], v[140:141], v[164:165]
	v_pk_mul_f32 v[146:147], v[146:147], v[164:165]
	v_pk_mul_f32 v[152:153], v[152:153], v[164:165]
	v_pk_mul_f32 v[158:159], v[158:159], v[164:165]
	v_exp_f32_e32 v140, v140
	v_exp_f32_e32 v141, v141
	v_exp_f32_e32 v146, v146
	v_exp_f32_e32 v147, v147
	v_exp_f32_e32 v152, v152
	v_exp_f32_e32 v153, v153
	v_exp_f32_e32 v158, v158
	v_exp_f32_e32 v159, v159
	v_pk_add_f32 v[140:141], v[140:141], 1.0 op_sel_hi:[1,0]
	v_pk_add_f32 v[146:147], v[146:147], 1.0 op_sel_hi:[1,0]
	v_pk_add_f32 v[152:153], v[152:153], 1.0 op_sel_hi:[1,0]
	v_pk_add_f32 v[158:159], v[158:159], 1.0 op_sel_hi:[1,0]
	v_rcp_f32_e32 v140, v140
	v_rcp_f32_e32 v141, v141
	v_rcp_f32_e32 v146, v146
	v_rcp_f32_e32 v147, v147
	v_rcp_f32_e32 v152, v152
	v_rcp_f32_e32 v153, v153
	v_rcp_f32_e32 v158, v158
	v_rcp_f32_e32 v159, v159
	v_pk_fma_f32 v[140:141], v[140:141], 2.0, 1.0 op_sel_hi:[1,0,0] neg_lo:[1,0,0] neg_hi:[1,0,0]
	v_pk_fma_f32 v[146:147], v[146:147], 2.0, 1.0 op_sel_hi:[1,0,0] neg_lo:[1,0,0] neg_hi:[1,0,0]
	v_pk_fma_f32 v[152:153], v[152:153], 2.0, 1.0 op_sel_hi:[1,0,0] neg_lo:[1,0,0] neg_hi:[1,0,0]
	v_pk_fma_f32 v[158:159], v[158:159], 2.0, 1.0 op_sel_hi:[1,0,0] neg_lo:[1,0,0] neg_hi:[1,0,0]
	v_cvt_pk_bf16_f32 v160, v140, v141
	v_cvt_pk_bf16_f32 v161, v146, v147
	v_cvt_pk_bf16_f32 v162, v152, v153
	v_cvt_pk_bf16_f32 v163, v158, v159
	ds_write_b128 v223, v[160:163] offset:16384
	s_waitcnt lgkmcnt(2)
	v_lshlrev_b32_e32 v136, 16, v180
	v_and_b32_e32 v137, 0xffff0000, v180
	v_lshlrev_b32_e32 v138, 16, v188
	v_and_b32_e32 v139, 0xffff0000, v188
	v_lshlrev_b32_e32 v140, 16, v184
	v_and_b32_e32 v141, 0xffff0000, v184
	v_lshlrev_b32_e32 v142, 16, v181
	v_and_b32_e32 v143, 0xffff0000, v181
	v_lshlrev_b32_e32 v144, 16, v189
	v_and_b32_e32 v145, 0xffff0000, v189
	v_lshlrev_b32_e32 v146, 16, v185
	v_and_b32_e32 v147, 0xffff0000, v185
	v_lshlrev_b32_e32 v148, 16, v182
	v_and_b32_e32 v149, 0xffff0000, v182
	v_lshlrev_b32_e32 v150, 16, v190
	v_and_b32_e32 v151, 0xffff0000, v190
	v_lshlrev_b32_e32 v152, 16, v186
	v_and_b32_e32 v153, 0xffff0000, v186
	v_lshlrev_b32_e32 v154, 16, v183
	v_and_b32_e32 v155, 0xffff0000, v183
	v_lshlrev_b32_e32 v156, 16, v191
	v_and_b32_e32 v157, 0xffff0000, v191
	v_lshlrev_b32_e32 v158, 16, v187
	v_and_b32_e32 v159, 0xffff0000, v187
	v_pk_add_f32 v[136:137], v[138:139], v[136:137]
	v_pk_add_f32 v[142:143], v[144:145], v[142:143]
	v_pk_add_f32 v[148:149], v[150:151], v[148:149]
	v_pk_add_f32 v[154:155], v[156:157], v[154:155]
	v_pk_fma_f32 v[136:137], v[136:137], 0.5, v[140:141] op_sel_hi:[1,0,1] neg_lo:[0,0,1] neg_hi:[0,0,1]
	v_pk_fma_f32 v[142:143], v[142:143], 0.5, v[146:147] op_sel_hi:[1,0,1] neg_lo:[0,0,1] neg_hi:[0,0,1]
	v_pk_fma_f32 v[148:149], v[148:149], 0.5, v[152:153] op_sel_hi:[1,0,1] neg_lo:[0,0,1] neg_hi:[0,0,1]
	v_pk_fma_f32 v[154:155], v[154:155], 0.5, v[158:159] op_sel_hi:[1,0,1] neg_lo:[0,0,1] neg_hi:[0,0,1]
	v_pk_fma_f32 v[140:141], v[200:201], v[136:137], v[140:141]
	v_pk_fma_f32 v[146:147], v[202:203], v[142:143], v[146:147]
	v_pk_fma_f32 v[152:153], v[204:205], v[148:149], v[152:153]
	v_pk_fma_f32 v[158:159], v[206:207], v[154:155], v[158:159]
	v_cvt_pk_bf16_f32 v216, v140, v141
	v_cvt_pk_bf16_f32 v217, v146, v147
	v_cvt_pk_bf16_f32 v218, v152, v153
	v_cvt_pk_bf16_f32 v219, v158, v159
	ds_write_b128 v223, v[216:219] offset:24576
	v_and_b32_e32 v160, 15, v1
	v_and_b32_e32 v161, -16, v1
	v_or_b32_e32 v162, s0, v160
	v_lshrrev_b32_e32 v163, 2, v1
	v_lshl_add_u32 v161, v162, 7, v161
	ds_read_b128 v[136:139], v161 offset:16384
	ds_read_b128 v[140:143], v161 offset:16448
	ds_read_b128 v[144:147], v161 offset:24576
	ds_read_b128 v[148:151], v161 offset:24640
	v_lshlrev_b32_e32 v162, 2, v160
	v_and_b32_e32 v163, 0x1fffffc, v163
	v_add_u32_e32 v162, 0x22400, v162
	v_add_lshl_u32 v163, v163, s0, 7
	ds_read2_b32 v[152:153], v162 offset0:64 offset1:80
	ds_read2_b32 v[154:155], v162 offset0:96 offset1:112
	ds_read2_b32 v[156:157], v162 offset0:128 offset1:144
	ds_read2_b32 v[158:159], v162 offset0:160 offset1:176
	v_lshl_add_u32 v163, v160, 1, v163
	v_mov_b32_e32 v164, 0xbfb8aa3b
	v_mov_b32_e32 v165, 0xbfb8aa3b
	s_waitcnt vmcnt(8)
	s_waitcnt lgkmcnt(7)
	v_mfma_f32_16x16x32_bf16 v[168:171], v[136:139], v[34:37], 0
	v_mfma_f32_16x16x32_bf16 v[172:175], v[136:139], v[42:45], 0
	v_mfma_f32_16x16x32_bf16 v[176:179], v[136:139], v[50:53], 0
	v_mfma_f32_16x16x32_bf16 v[180:183], v[136:139], v[58:61], 0
	s_waitcnt lgkmcnt(6)
	v_mfma_f32_16x16x32_bf16 v[168:171], v[140:143], v[38:41], v[168:171]
	v_mfma_f32_16x16x32_bf16 v[172:175], v[140:143], v[46:49], v[172:175]
	v_mfma_f32_16x16x32_bf16 v[176:179], v[140:143], v[54:57], v[176:179]
	v_mfma_f32_16x16x32_bf16 v[180:183], v[140:143], v[62:65], v[180:183]
	s_waitcnt vmcnt(0)
	s_waitcnt lgkmcnt(5)
	v_mfma_f32_16x16x32_bf16 v[184:187], v[144:147], v[66:69], 0
	v_mfma_f32_16x16x32_bf16 v[188:191], v[144:147], v[74:77], 0
	v_mfma_f32_16x16x32_bf16 v[192:195], v[144:147], v[82:85], 0
	v_mfma_f32_16x16x32_bf16 v[196:199], v[144:147], v[90:93], 0
	s_waitcnt lgkmcnt(4)
	v_mfma_f32_16x16x32_bf16 v[184:187], v[148:151], v[70:73], v[184:187]
	v_mfma_f32_16x16x32_bf16 v[188:191], v[148:151], v[78:81], v[188:191]
	v_mfma_f32_16x16x32_bf16 v[192:195], v[148:151], v[86:89], v[192:195]
	v_mfma_f32_16x16x32_bf16 v[196:199], v[148:151], v[94:97], v[196:199]
	s_waitcnt lgkmcnt(0)
	v_pk_add_f32 v[168:169], v[168:169], v[152:153] op_sel_hi:[1,0]
	v_pk_add_f32 v[170:171], v[170:171], v[152:153] op_sel_hi:[1,0]
	v_pk_add_f32 v[172:173], v[172:173], v[152:153] op_sel:[0,1] op_sel_hi:[1,1]
	v_pk_add_f32 v[174:175], v[174:175], v[152:153] op_sel:[0,1] op_sel_hi:[1,1]
	v_pk_add_f32 v[176:177], v[176:177], v[154:155] op_sel_hi:[1,0]
	v_pk_add_f32 v[178:179], v[178:179], v[154:155] op_sel_hi:[1,0]
	v_pk_add_f32 v[180:181], v[180:181], v[154:155] op_sel:[0,1] op_sel_hi:[1,1]
	v_pk_add_f32 v[182:183], v[182:183], v[154:155] op_sel:[0,1] op_sel_hi:[1,1]
	v_pk_mul_f32 v[168:169], v[168:169], v[164:165]
	v_pk_mul_f32 v[170:171], v[170:171], v[164:165]
	v_pk_mul_f32 v[172:173], v[172:173], v[164:165]
	v_pk_mul_f32 v[174:175], v[174:175], v[164:165]
	v_pk_mul_f32 v[176:177], v[176:177], v[164:165]
	v_pk_mul_f32 v[178:179], v[178:179], v[164:165]
	v_pk_mul_f32 v[180:181], v[180:181], v[164:165]
	v_pk_mul_f32 v[182:183], v[182:183], v[164:165]
	v_exp_f32_e32 v168, v168
	v_exp_f32_e32 v169, v169
	v_exp_f32_e32 v170, v170
	v_exp_f32_e32 v171, v171
	v_exp_f32_e32 v172, v172
	v_exp_f32_e32 v173, v173
	v_exp_f32_e32 v174, v174
	v_exp_f32_e32 v175, v175
	v_exp_f32_e32 v176, v176
	v_exp_f32_e32 v177, v177
	v_exp_f32_e32 v178, v178
	v_exp_f32_e32 v179, v179
	v_exp_f32_e32 v180, v180
	v_exp_f32_e32 v181, v181
	v_exp_f32_e32 v182, v182
	v_exp_f32_e32 v183, v183
	v_pk_add_f32 v[168:169], v[168:169], 1.0 op_sel_hi:[1,0]
	v_pk_add_f32 v[170:171], v[170:171], 1.0 op_sel_hi:[1,0]
	v_pk_add_f32 v[172:173], v[172:173], 1.0 op_sel_hi:[1,0]
	v_pk_add_f32 v[174:175], v[174:175], 1.0 op_sel_hi:[1,0]
	v_pk_add_f32 v[176:177], v[176:177], 1.0 op_sel_hi:[1,0]
	v_pk_add_f32 v[178:179], v[178:179], 1.0 op_sel_hi:[1,0]
	v_pk_add_f32 v[180:181], v[180:181], 1.0 op_sel_hi:[1,0]
	v_pk_add_f32 v[182:183], v[182:183], 1.0 op_sel_hi:[1,0]
	v_rcp_f32_e32 v168, v168
	v_rcp_f32_e32 v169, v169
	v_rcp_f32_e32 v170, v170
	v_rcp_f32_e32 v171, v171
	v_rcp_f32_e32 v172, v172
	v_rcp_f32_e32 v173, v173
	v_rcp_f32_e32 v174, v174
	v_rcp_f32_e32 v175, v175
	v_rcp_f32_e32 v176, v176
	v_rcp_f32_e32 v177, v177
	v_rcp_f32_e32 v178, v178
	v_rcp_f32_e32 v179, v179
	v_rcp_f32_e32 v180, v180
	v_rcp_f32_e32 v181, v181
	v_rcp_f32_e32 v182, v182
	v_rcp_f32_e32 v183, v183
	v_fma_mixlo_f16 v168, v168, s47, 0
	v_fma_mixlo_f16 v169, v169, s47, 0
	v_fma_mixlo_f16 v170, v170, s47, 0
	v_fma_mixlo_f16 v171, v171, s47, 0
	v_fma_mixlo_f16 v172, v172, s47, 0
	v_fma_mixlo_f16 v173, v173, s47, 0
	v_fma_mixlo_f16 v174, v174, s47, 0
	v_fma_mixlo_f16 v175, v175, s47, 0
	v_fma_mixlo_f16 v176, v176, s47, 0
	v_fma_mixlo_f16 v177, v177, s47, 0
	v_fma_mixlo_f16 v178, v178, s47, 0
	v_fma_mixlo_f16 v179, v179, s47, 0
	v_fma_mixlo_f16 v180, v180, s47, 0
	v_fma_mixlo_f16 v181, v181, s47, 0
	v_fma_mixlo_f16 v182, v182, s47, 0
	v_fma_mixlo_f16 v183, v183, s47, 0
	ds_write_b16 v163, v168 offset:16384
	ds_write_b16 v163, v169 offset:16512
	ds_write_b16 v163, v170 offset:16640
	ds_write_b16 v163, v171 offset:16768
	ds_write_b16 v163, v172 offset:16416
	ds_write_b16 v163, v173 offset:16544
	ds_write_b16 v163, v174 offset:16672
	ds_write_b16 v163, v175 offset:16800
	ds_write_b16 v163, v176 offset:16448
	ds_write_b16 v163, v177 offset:16576
	ds_write_b16 v163, v178 offset:16704
	ds_write_b16 v163, v179 offset:16832
	ds_write_b16 v163, v180 offset:16480
	ds_write_b16 v163, v181 offset:16608
	ds_write_b16 v163, v182 offset:16736
	ds_write_b16 v163, v183 offset:16864
	v_pk_add_f32 v[184:185], v[184:185], v[156:157] op_sel_hi:[1,0]
	v_pk_add_f32 v[186:187], v[186:187], v[156:157] op_sel_hi:[1,0]
	v_pk_add_f32 v[188:189], v[188:189], v[156:157] op_sel:[0,1] op_sel_hi:[1,1]
	v_pk_add_f32 v[190:191], v[190:191], v[156:157] op_sel:[0,1] op_sel_hi:[1,1]
	v_pk_add_f32 v[192:193], v[192:193], v[158:159] op_sel_hi:[1,0]
	v_pk_add_f32 v[194:195], v[194:195], v[158:159] op_sel_hi:[1,0]
	v_pk_add_f32 v[196:197], v[196:197], v[158:159] op_sel:[0,1] op_sel_hi:[1,1]
	v_pk_add_f32 v[198:199], v[198:199], v[158:159] op_sel:[0,1] op_sel_hi:[1,1]
	v_pk_mul_f32 v[184:185], v[184:185], v[164:165]
	v_pk_mul_f32 v[186:187], v[186:187], v[164:165]
	v_pk_mul_f32 v[188:189], v[188:189], v[164:165]
	v_pk_mul_f32 v[190:191], v[190:191], v[164:165]
	v_pk_mul_f32 v[192:193], v[192:193], v[164:165]
	v_pk_mul_f32 v[194:195], v[194:195], v[164:165]
	v_pk_mul_f32 v[196:197], v[196:197], v[164:165]
	v_pk_mul_f32 v[198:199], v[198:199], v[164:165]
	v_exp_f32_e32 v184, v184
	v_exp_f32_e32 v185, v185
	v_exp_f32_e32 v186, v186
	v_exp_f32_e32 v187, v187
	v_exp_f32_e32 v188, v188
	v_exp_f32_e32 v189, v189
	v_exp_f32_e32 v190, v190
	v_exp_f32_e32 v191, v191
	v_exp_f32_e32 v192, v192
	v_exp_f32_e32 v193, v193
	v_exp_f32_e32 v194, v194
	v_exp_f32_e32 v195, v195
	v_exp_f32_e32 v196, v196
	v_exp_f32_e32 v197, v197
	v_exp_f32_e32 v198, v198
	v_exp_f32_e32 v199, v199
	v_pk_add_f32 v[184:185], v[184:185], 1.0 op_sel_hi:[1,0]
	v_pk_add_f32 v[186:187], v[186:187], 1.0 op_sel_hi:[1,0]
	v_pk_add_f32 v[188:189], v[188:189], 1.0 op_sel_hi:[1,0]
	v_pk_add_f32 v[190:191], v[190:191], 1.0 op_sel_hi:[1,0]
	v_pk_add_f32 v[192:193], v[192:193], 1.0 op_sel_hi:[1,0]
	v_pk_add_f32 v[194:195], v[194:195], 1.0 op_sel_hi:[1,0]
	v_pk_add_f32 v[196:197], v[196:197], 1.0 op_sel_hi:[1,0]
	v_pk_add_f32 v[198:199], v[198:199], 1.0 op_sel_hi:[1,0]
	v_rcp_f32_e32 v184, v184
	v_rcp_f32_e32 v185, v185
	v_rcp_f32_e32 v186, v186
	v_rcp_f32_e32 v187, v187
	v_rcp_f32_e32 v188, v188
	v_rcp_f32_e32 v189, v189
	v_rcp_f32_e32 v190, v190
	v_rcp_f32_e32 v191, v191
	v_rcp_f32_e32 v192, v192
	v_rcp_f32_e32 v193, v193
	v_rcp_f32_e32 v194, v194
	v_rcp_f32_e32 v195, v195
	v_rcp_f32_e32 v196, v196
	v_rcp_f32_e32 v197, v197
	v_rcp_f32_e32 v198, v198
	v_rcp_f32_e32 v199, v199
	v_cvt_pk_f16_f32 v184, v184, v185
	v_cvt_pk_f16_f32 v186, v186, v187
	v_cvt_pk_f16_f32 v188, v188, v189
	v_cvt_pk_f16_f32 v190, v190, v191
	v_cvt_pk_f16_f32 v192, v192, v193
	v_cvt_pk_f16_f32 v194, v194, v195
	v_cvt_pk_f16_f32 v196, v196, v197
	v_cvt_pk_f16_f32 v198, v198, v199
	ds_write_b16 v163, v184 offset:24576
	ds_write_b16_d16_hi v163, v184 offset:24704
	ds_write_b16 v163, v186 offset:24832
	ds_write_b16_d16_hi v163, v186 offset:24960
	ds_write_b16 v163, v188 offset:24608
	ds_write_b16_d16_hi v163, v188 offset:24736
	ds_write_b16 v163, v190 offset:24864
	ds_write_b16_d16_hi v163, v190 offset:24992
	ds_write_b16 v163, v192 offset:24640
	ds_write_b16_d16_hi v163, v192 offset:24768
	ds_write_b16 v163, v194 offset:24896
	ds_write_b16_d16_hi v163, v194 offset:25024
	ds_write_b16 v163, v196 offset:24672
	ds_write_b16_d16_hi v163, v196 offset:24800
	ds_write_b16 v163, v198 offset:24928
	ds_write_b16_d16_hi v163, v198 offset:25056
